# NSA compressed pass 2: K fragments read from LDS once per block and shared by both query groups
# baseline (speedup 1.0000x reference)
.LBB0_1076:
	s_add_i32 s10, s40, 0
	v_add_u32_e32 v87, s10, v163
	v_add_u32_e32 v86, s10, v211
	v_add_u32_e32 v88, s10, v165
	v_add_u32_e32 v89, s10, v212
	ds_read_b128 v[116:119], v87
	ds_read_b128 v[120:123], v86
	ds_read_b128 v[124:127], v88
	ds_read_b128 v[128:131], v89
	ds_read_b128 v[132:135], v87 offset:4096
	ds_read_b128 v[136:139], v86 offset:4096
	ds_read_b128 v[140:143], v88 offset:4096
	ds_read_b128 v[224:227], v89 offset:4096
	s_waitcnt lgkmcnt(6)
	v_mfma_f32_16x16x32_bf16 v[90:93], v[116:119], v[14:17], 0
	v_mfma_f32_16x16x32_bf16 v[90:93], v[120:123], v[2:5], v[90:93]
	s_waitcnt lgkmcnt(4)
	v_mfma_f32_16x16x32_bf16 v[58:61], v[124:127], v[14:17], 0
	v_mfma_f32_16x16x32_bf16 v[58:61], v[128:131], v[2:5], v[58:61]
	s_waitcnt lgkmcnt(2)
	v_mfma_f32_16x16x32_bf16 v[54:57], v[132:135], v[14:17], 0
	v_mfma_f32_16x16x32_bf16 v[54:57], v[136:139], v[2:5], v[54:57]
	s_waitcnt lgkmcnt(0)
	v_mfma_f32_16x16x32_bf16 v[50:53], v[140:143], v[14:17], 0
	v_mfma_f32_16x16x32_bf16 v[50:53], v[224:227], v[2:5], v[50:53]
	v_cmp_lt_i32_e32 vcc, 0, v84
	s_nop 0
	v_sub_f32_e32 v90, v90, v81
	v_sub_f32_e32 v91, v91, v81
	v_exp_f32_e32 v90, v90
	v_exp_f32_e32 v91, v91
	v_sub_f32_e32 v92, v92, v81
	v_sub_f32_e32 v93, v93, v81
	v_exp_f32_e32 v92, v92
	v_exp_f32_e32 v93, v93
	v_mul_f32_e64 v94, v66, v90
	v_mul_f32_e64 v95, v67, v91
	v_cndmask_b32_e32 v90, 0, v95, vcc
	v_cmp_lt_i32_e32 vcc, -1, v84
	s_nop 1
	v_cndmask_b32_e32 v91, 0, v94, vcc
	v_add_f32_e32 v94, 0, v91
	v_add_f32_e32 v96, v90, v94
	v_pk_mul_f32 v[94:95], v[66:67], v[92:93]
	v_cmp_lt_i32_e32 vcc, 2, v84
	s_nop 1
	v_cndmask_b32_e32 v92, 0, v95, vcc
	v_cmp_lt_i32_e32 vcc, 1, v84
	s_nop 1
	v_cndmask_b32_e32 v93, 0, v94, vcc
	v_add_f32_e32 v94, v93, v96
	v_add_f32_e32 v94, v92, v94
	s_nop 1
	v_add_f32_dpp v94, v94, v94 quad_perm:[1,0,3,2] row_mask:0xf bank_mask:0xf bound_ctrl:1
	s_nop 1
	v_mov_b32_dpp v95, v94 quad_perm:[2,3,0,1] row_mask:0xf bank_mask:0xf bound_ctrl:1
	s_and_saveexec_b64 s[6:7], s[30:31]
	v_add_f32_e32 v94, v94, v95
	ds_write_b32 v0, v94
	s_or_b64 exec, exec, s[6:7]
	v_sub_f32_e32 v58, v58, v81
	v_sub_f32_e32 v59, v59, v81
	v_exp_f32_e32 v58, v58
	v_exp_f32_e32 v59, v59
	v_cmp_lt_i32_e32 vcc, 4, v84
	v_pk_mul_f32 v[94:95], v[66:67], v[58:59]
	v_sub_f32_e32 v59, v60, v81
	v_exp_f32_e32 v60, v59
	v_sub_f32_e32 v59, v61, v81
	v_exp_f32_e32 v61, v59
	v_cndmask_b32_e32 v58, 0, v95, vcc
	v_cmp_lt_i32_e32 vcc, 3, v84
	s_nop 1
	v_cndmask_b32_e32 v59, 0, v94, vcc
	v_add_f32_e32 v94, 0, v59
	v_add_f32_e32 v96, v58, v94
	v_pk_mul_f32 v[94:95], v[66:67], v[60:61]
	v_cmp_lt_i32_e32 vcc, 6, v84
	s_nop 1
	v_cndmask_b32_e32 v60, 0, v95, vcc
	v_cmp_lt_i32_e32 vcc, 5, v84
	s_nop 1
	v_cndmask_b32_e32 v61, 0, v94, vcc
	v_add_f32_e32 v94, v61, v96
	v_add_f32_e32 v94, v60, v94
	s_nop 1
	v_add_f32_dpp v94, v94, v94 quad_perm:[1,0,3,2] row_mask:0xf bank_mask:0xf bound_ctrl:1
	s_nop 1
	v_mov_b32_dpp v95, v94 quad_perm:[2,3,0,1] row_mask:0xf bank_mask:0xf bound_ctrl:1
	s_and_saveexec_b64 s[6:7], s[30:31]
	v_add_f32_e32 v94, v94, v95
	ds_write_b32 v0, v94 offset:4
	s_or_b64 exec, exec, s[6:7]
	v_sub_f32_e32 v54, v54, v81
	v_sub_f32_e32 v55, v55, v81
	v_exp_f32_e32 v54, v54
	v_exp_f32_e32 v55, v55
	v_cmp_lt_i32_e32 vcc, 32, v84
	v_pk_mul_f32 v[94:95], v[66:67], v[54:55]
	v_sub_f32_e32 v55, v56, v81
	v_exp_f32_e32 v56, v55
	v_sub_f32_e32 v55, v57, v81
	v_exp_f32_e32 v57, v55
	v_cndmask_b32_e32 v54, 0, v95, vcc
	v_cmp_lt_i32_e32 vcc, 31, v84
	s_nop 1
	v_cndmask_b32_e32 v55, 0, v94, vcc
	v_add_f32_e32 v94, 0, v55
	v_add_f32_e32 v96, v54, v94
	v_pk_mul_f32 v[94:95], v[66:67], v[56:57]
	v_cmp_lt_i32_e32 vcc, 34, v84
	s_nop 1
	v_cndmask_b32_e32 v56, 0, v95, vcc
	v_cmp_lt_i32_e32 vcc, 33, v84
	s_nop 1
	v_cndmask_b32_e32 v57, 0, v94, vcc
	v_add_f32_e32 v94, v57, v96
	v_add_f32_e32 v94, v56, v94
	s_nop 1
	v_add_f32_dpp v94, v94, v94 quad_perm:[1,0,3,2] row_mask:0xf bank_mask:0xf bound_ctrl:1
	s_nop 1
	v_mov_b32_dpp v95, v94 quad_perm:[2,3,0,1] row_mask:0xf bank_mask:0xf bound_ctrl:1
	s_and_saveexec_b64 s[6:7], s[30:31]
	v_add_f32_e32 v94, v94, v95
	ds_write_b32 v0, v94 offset:32
	s_or_b64 exec, exec, s[6:7]
	v_sub_f32_e32 v50, v50, v81
	v_sub_f32_e32 v51, v51, v81
	v_exp_f32_e32 v50, v50
	v_exp_f32_e32 v51, v51
	v_cmp_lt_i32_e32 vcc, 36, v84
	v_pk_mul_f32 v[94:95], v[66:67], v[50:51]
	v_sub_f32_e32 v51, v52, v81
	v_exp_f32_e32 v52, v51
	v_sub_f32_e32 v51, v53, v81
	v_exp_f32_e32 v53, v51
	v_cndmask_b32_e32 v50, 0, v95, vcc
	v_cmp_lt_i32_e32 vcc, 35, v84
	s_nop 1
	v_cndmask_b32_e32 v51, 0, v94, vcc
	v_add_f32_e32 v94, 0, v51
	v_add_f32_e32 v96, v50, v94
	v_pk_mul_f32 v[94:95], v[66:67], v[52:53]
	v_cmp_lt_i32_e32 vcc, 38, v84
	s_nop 1
	v_cndmask_b32_e32 v52, 0, v95, vcc
	v_cmp_lt_i32_e32 vcc, 37, v84
	s_nop 1
	v_cndmask_b32_e32 v53, 0, v94, vcc
	v_add_f32_e32 v94, v53, v96
	v_add_f32_e32 v94, v52, v94
	s_nop 1
	v_add_f32_dpp v94, v94, v94 quad_perm:[1,0,3,2] row_mask:0xf bank_mask:0xf bound_ctrl:1
	s_nop 1
	v_mov_b32_dpp v95, v94 quad_perm:[2,3,0,1] row_mask:0xf bank_mask:0xf bound_ctrl:1
	s_and_saveexec_b64 s[6:7], s[30:31]
	v_add_f32_e32 v94, v94, v95
	ds_write_b32 v0, v94 offset:36
	s_or_b64 exec, exec, s[6:7]
	v_cvt_pk_bf16_f32 v94, v91, v90
	v_add_u32_e32 v90, s10, v215
	v_cvt_pk_bf16_f32 v96, v59, v58
	v_cvt_pk_bf16_f32 v97, v61, v60
	ds_read_b128 v[58:61], v90 offset:8192
	v_add_u32_e32 v91, s10, v216
	v_cvt_pk_bf16_f32 v54, v55, v54
	v_cvt_pk_bf16_f32 v55, v57, v56
	v_cvt_pk_bf16_f32 v56, v51, v50
	v_cvt_pk_bf16_f32 v57, v53, v52
	ds_read_b128 v[50:53], v91 offset:8192
	v_cvt_pk_bf16_f32 v95, v93, v92
	v_cmp_lt_i32_e32 vcc, 0, v83
	s_waitcnt lgkmcnt(1)
	v_mfma_f32_16x16x32_bf16 v[46:49], v[58:61], v[94:97], v[46:49]
	ds_read_b128 v[58:61], v90 offset:10240
	s_waitcnt lgkmcnt(1)
	v_mfma_f32_16x16x32_bf16 v[46:49], v[50:53], v[54:57], v[46:49]
	ds_read_b128 v[50:53], v91 offset:10240
	s_waitcnt lgkmcnt(1)
	v_mfma_f32_16x16x32_bf16 v[34:37], v[58:61], v[94:97], v[34:37]
	ds_read_b128 v[58:61], v90 offset:12288
	s_waitcnt lgkmcnt(1)
	v_mfma_f32_16x16x32_bf16 v[34:37], v[50:53], v[54:57], v[34:37]
	ds_read_b128 v[50:53], v91 offset:12288
	s_waitcnt lgkmcnt(1)
	v_mfma_f32_16x16x32_bf16 v[42:45], v[58:61], v[94:97], v[42:45]
	ds_read_b128 v[58:61], v90 offset:14336
	s_waitcnt lgkmcnt(1)
	v_mfma_f32_16x16x32_bf16 v[42:45], v[50:53], v[54:57], v[42:45]
	ds_read_b128 v[50:53], v91 offset:14336
	s_waitcnt lgkmcnt(1)
	v_mfma_f32_16x16x32_bf16 v[38:41], v[58:61], v[94:97], v[38:41]
	s_waitcnt lgkmcnt(0)
	v_mfma_f32_16x16x32_bf16 v[38:41], v[50:53], v[54:57], v[38:41]
	v_mfma_f32_16x16x32_bf16 v[92:95], v[116:119], v[10:13], 0
	v_mfma_f32_16x16x32_bf16 v[92:95], v[120:123], v[6:9], v[92:95]
	v_mfma_f32_16x16x32_bf16 v[58:61], v[124:127], v[10:13], 0
	v_mfma_f32_16x16x32_bf16 v[58:61], v[128:131], v[6:9], v[58:61]
	v_mfma_f32_16x16x32_bf16 v[54:57], v[132:135], v[10:13], 0
	v_mfma_f32_16x16x32_bf16 v[54:57], v[136:139], v[6:9], v[54:57]
	v_mfma_f32_16x16x32_bf16 v[50:53], v[140:143], v[10:13], 0
	v_mfma_f32_16x16x32_bf16 v[50:53], v[224:227], v[6:9], v[50:53]
	s_nop 1
	v_sub_f32_e32 v86, v92, v82
	v_sub_f32_e32 v87, v93, v82
	v_exp_f32_e32 v86, v86
	v_exp_f32_e32 v87, v87
	s_nop 0
	v_pk_mul_f32 v[88:89], v[68:69], v[86:87]
	s_nop 0
	v_cndmask_b32_e32 v86, 0, v89, vcc
	v_cmp_lt_i32_e32 vcc, -1, v83
	v_sub_f32_e32 v89, v95, v82
	v_exp_f32_e32 v89, v89
	v_cndmask_b32_e32 v87, 0, v88, vcc
	v_add_f32_e32 v88, 0, v87
	v_add_f32_e32 v96, v86, v88
	v_sub_f32_e32 v88, v94, v82
	v_exp_f32_e32 v88, v88
	v_cmp_lt_i32_e32 vcc, 2, v83
	v_pk_mul_f32 v[92:93], v[68:69], v[88:89]
	s_nop 0
	v_cndmask_b32_e32 v88, 0, v93, vcc
	v_cmp_lt_i32_e32 vcc, 1, v83
	s_nop 1
	v_cndmask_b32_e32 v89, 0, v92, vcc
	v_add_f32_e32 v92, v89, v96
	v_add_f32_e32 v92, v88, v92
	s_nop 1
	v_add_f32_dpp v92, v92, v92 quad_perm:[1,0,3,2] row_mask:0xf bank_mask:0xf bound_ctrl:1
	s_nop 1
	v_mov_b32_dpp v93, v92 quad_perm:[2,3,0,1] row_mask:0xf bank_mask:0xf bound_ctrl:1
	s_and_saveexec_b64 s[6:7], s[30:31]
	v_add_f32_e32 v92, v92, v93
	ds_write_b32 v0, v92 offset:4096
	s_or_b64 exec, exec, s[6:7]
	v_sub_f32_e32 v58, v58, v82
	v_sub_f32_e32 v59, v59, v82
	v_exp_f32_e32 v58, v58
	v_exp_f32_e32 v59, v59
	v_cmp_lt_i32_e32 vcc, 4, v83
	v_pk_mul_f32 v[92:93], v[68:69], v[58:59]
	v_sub_f32_e32 v59, v60, v82
	v_exp_f32_e32 v60, v59
	v_sub_f32_e32 v59, v61, v82
	v_exp_f32_e32 v61, v59
	v_cndmask_b32_e32 v58, 0, v93, vcc
	v_cmp_lt_i32_e32 vcc, 3, v83
	s_nop 1
	v_cndmask_b32_e32 v59, 0, v92, vcc
	v_add_f32_e32 v92, 0, v59
	v_add_f32_e32 v94, v58, v92
	v_pk_mul_f32 v[92:93], v[68:69], v[60:61]
	v_cmp_lt_i32_e32 vcc, 6, v83
	s_nop 1
	v_cndmask_b32_e32 v60, 0, v93, vcc
	v_cmp_lt_i32_e32 vcc, 5, v83
	s_nop 1
	v_cndmask_b32_e32 v61, 0, v92, vcc
	v_add_f32_e32 v92, v61, v94
	v_add_f32_e32 v92, v60, v92
	s_nop 1
	v_add_f32_dpp v92, v92, v92 quad_perm:[1,0,3,2] row_mask:0xf bank_mask:0xf bound_ctrl:1
	s_nop 1
	v_mov_b32_dpp v93, v92 quad_perm:[2,3,0,1] row_mask:0xf bank_mask:0xf bound_ctrl:1
	s_and_saveexec_b64 s[6:7], s[30:31]
	v_add_f32_e32 v92, v92, v93
	ds_write_b32 v0, v92 offset:4100
	s_or_b64 exec, exec, s[6:7]
	v_sub_f32_e32 v54, v54, v82
	v_sub_f32_e32 v55, v55, v82
	v_exp_f32_e32 v54, v54
	v_exp_f32_e32 v55, v55
	v_cmp_lt_i32_e32 vcc, 32, v83
	v_pk_mul_f32 v[92:93], v[68:69], v[54:55]
	v_sub_f32_e32 v55, v56, v82
	v_exp_f32_e32 v56, v55
	v_sub_f32_e32 v55, v57, v82
	v_exp_f32_e32 v57, v55
	v_cndmask_b32_e32 v54, 0, v93, vcc
	v_cmp_lt_i32_e32 vcc, 31, v83
	s_nop 1
	v_cndmask_b32_e32 v55, 0, v92, vcc
	v_add_f32_e32 v92, 0, v55
	v_add_f32_e32 v94, v54, v92
	v_pk_mul_f32 v[92:93], v[68:69], v[56:57]
	v_cmp_lt_i32_e32 vcc, 34, v83
	s_nop 1
	v_cndmask_b32_e32 v56, 0, v93, vcc
	v_cmp_lt_i32_e32 vcc, 33, v83
	s_nop 1
	v_cndmask_b32_e32 v57, 0, v92, vcc
	v_add_f32_e32 v92, v57, v94
	v_add_f32_e32 v92, v56, v92
	s_nop 1
	v_add_f32_dpp v92, v92, v92 quad_perm:[1,0,3,2] row_mask:0xf bank_mask:0xf bound_ctrl:1
	s_nop 1
	v_mov_b32_dpp v93, v92 quad_perm:[2,3,0,1] row_mask:0xf bank_mask:0xf bound_ctrl:1
	s_and_saveexec_b64 s[6:7], s[30:31]
	v_add_f32_e32 v92, v92, v93
	ds_write_b32 v0, v92 offset:4128
	s_or_b64 exec, exec, s[6:7]
	v_sub_f32_e32 v50, v50, v82
	v_sub_f32_e32 v51, v51, v82
	v_exp_f32_e32 v50, v50
	v_exp_f32_e32 v51, v51
	v_cmp_lt_i32_e32 vcc, 36, v83
	v_pk_mul_f32 v[92:93], v[68:69], v[50:51]
	v_sub_f32_e32 v51, v52, v82
	v_exp_f32_e32 v52, v51
	v_sub_f32_e32 v51, v53, v82
	v_exp_f32_e32 v53, v51
	v_cndmask_b32_e32 v50, 0, v93, vcc
	v_cmp_lt_i32_e32 vcc, 35, v83
	s_nop 1
	v_cndmask_b32_e32 v51, 0, v92, vcc
	v_add_f32_e32 v92, 0, v51
	v_add_f32_e32 v94, v50, v92
	v_pk_mul_f32 v[92:93], v[68:69], v[52:53]
	v_cmp_lt_i32_e32 vcc, 38, v83
	s_nop 1
	v_cndmask_b32_e32 v52, 0, v93, vcc
	v_cmp_lt_i32_e32 vcc, 37, v83
	s_nop 1
	v_cndmask_b32_e32 v53, 0, v92, vcc
	v_add_f32_e32 v92, v53, v94
	v_add_f32_e32 v92, v52, v92
	s_nop 1
	v_add_f32_dpp v92, v92, v92 quad_perm:[1,0,3,2] row_mask:0xf bank_mask:0xf bound_ctrl:1
	s_nop 1
	v_mov_b32_dpp v93, v92 quad_perm:[2,3,0,1] row_mask:0xf bank_mask:0xf bound_ctrl:1
	s_and_saveexec_b64 s[6:7], s[30:31]
	s_cbranch_execz .LBB0_1071
	v_add_f32_e32 v92, v92, v93
	ds_write_b32 v0, v92 offset:4132
	s_branch .LBB0_1071
